# speedup vs baseline: 1.0126x; 1.0006x over previous
; template <int DQK>
; __device__ __forceinline__ void attn_unit64(LAS char* lds, const bf16x8 (&qa)[DQK / 16], const bf16x8 (&qb)[DQK / 16],
;                                             const bf16_t* Kg, int ldk, const bf16_t* Vg, int ldv, int t0, int t1, bf16_t* Oga, int ogb_off) {
;     ...
;         for (int kv = 0; kv < 2; ++kv) {
;             __builtin_amdgcn_iglp_opt(0);
;             f32x16 sa, sb;
; #pragma unroll
;             for (int i = 0; i < 16; ++i) { sa[i] = 0.f; sb[i] = 0.f; }
; #pragma unroll
;             for (int ds = 0; ds < DQK / 16; ++ds) {
;                 const bf16x8 kf = *(const LAS bf16x8*)(kb + kv * 32 * KP + ds * 32);
;                 sa = __builtin_amdgcn_mfma_f32_32x32x16_bf16(kf, qa[ds], sa, 0, 0, 0);
;                 sb = __builtin_amdgcn_mfma_f32_32x32x16_bf16(kf, qb[ds], sb, 0, 0, 0);
;             }
; #pragma unroll
;             for (int i = 0; i < 16; i += 2) { sa[i] = __builtin_amdgcn_exp2f(sa[i]); sa[i + 1] = __builtin_amdgcn_exp2f(sa[i + 1]); la0 += sa[i]; la1 += sa[i + 1];
;                                                sb[i] = __builtin_amdgcn_exp2f(sb[i]); sb[i + 1] = __builtin_amdgcn_exp2f(sb[i + 1]); lb0 += sb[i]; lb1 += sb[i + 1]; }
;             bf16x8 pa[2], pb[2]; pa[0] = pack8(sa, 0); pa[1] = pack8(sa, 1); pb[0] = pack8(sb, 0); pb[1] = pack8(sb, 1);
; #pragma unroll
;             for (int s2 = 0; s2 < 2; ++s2) {
;                 const int s = 2 * kv + s2;
;                 const s16x4 a0 = vtr(vb + (16 * s) * 64), a1 = vtr(vb + (16 * s + 8) * 64), c0 = vtr(vb + 4096 + (16 * s) * 64), c1 = vtr(vb + 4096 + (16 * s + 8) * 64);
;                 const bf16x8 va = (bf16x8){a0[0], a0[1], a0[2], a0[3], a1[0], a1[1], a1[2], a1[3]}, vc = (bf16x8){c0[0], c0[1], c0[2], c0[3], c1[0], c1[1], c1[2], c1[3]};
;                 oa0 = __builtin_amdgcn_mfma_f32_32x32x16_bf16(va, pa[s2], oa0, 0, 0, 0);
;                 oa1 = __builtin_amdgcn_mfma_f32_32x32x16_bf16(vc, pa[s2], oa1, 0, 0, 0);
;                 ob0 = __builtin_amdgcn_mfma_f32_32x32x16_bf16(va, pb[s2], ob0, 0, 0, 0);
;                 ob1 = __builtin_amdgcn_mfma_f32_32x32x16_bf16(vc, pb[s2], ob1, 0, 0, 0);
;             }
;         }
;         if (more) { const unsigned bo = (cur ^ 1) * BUF; *(LAS u32x4*)(lds + bo + kdst0) = kreg0; if (k2) *(LAS u32x4*)(lds + bo + kdst1) = kreg1; *(LAS u32x4*)(lds + bo + vdst) = vreg; }
;         __syncthreads();
.Lp11_g1_a0:
	global_load_dwordx4 v[104:107], v[180:181], off
	s_waitcnt lgkmcnt(2)
	v_mfma_f32_32x32x16_bf16 v[80:95], v[182:185], v[128:131], 0
	v_exp_f32_e32 v64, v64
	v_exp_f32_e32 v65, v65
	v_exp_f32_e32 v66, v66
	v_exp_f32_e32 v67, v67
	v_mfma_f32_32x32x16_bf16 v[80:95], v[186:189], v[124:127], v[80:95]
	v_exp_f32_e32 v68, v68
	v_exp_f32_e32 v69, v69
	v_cvt_pk_bf16_f32 v230, v64, v65
	v_cvt_pk_bf16_f32 v231, v66, v67
	v_mfma_f32_32x32x16_bf16 v[80:95], v[190:193], v[120:123], v[80:95]
	v_exp_f32_e32 v70, v70
	v_exp_f32_e32 v71, v71
	v_exp_f32_e32 v72, v72
	v_cvt_pk_bf16_f32 v232, v68, v69
	v_mfma_f32_32x32x16_bf16 v[80:95], v[194:197], v[116:119], v[80:95]
	v_exp_f32_e32 v73, v73
	v_exp_f32_e32 v74, v74
	v_cvt_pk_bf16_f32 v233, v70, v71
	v_exp_f32_e32 v75, v75
	v_mfma_f32_32x32x16_bf16 v[80:95], v[198:201], v[108:111], v[80:95]
	v_exp_f32_e32 v76, v76
	v_exp_f32_e32 v77, v77
	v_cvt_pk_bf16_f32 v234, v72, v73
	v_cvt_pk_bf16_f32 v235, v74, v75
	v_mfma_f32_32x32x16_bf16 v[80:95], v[202:205], v[112:115], v[80:95]
	v_exp_f32_e32 v78, v78
	v_exp_f32_e32 v79, v79
	v_cvt_pk_bf16_f32 v236, v76, v77
	v_cvt_pk_bf16_f32 v237, v78, v79
	v_mfma_f32_32x32x16_bf16 v[16:31], v[248:251], v[230:233], v[16:31]
	ds_read_b64_tr_b16 v[248:249], v239 offset:15360
	ds_read_b64_tr_b16 v[250:251], v239 offset:15872
	v_add_f32_e32 v172, v172, v64
	v_add_f32_e32 v173, v173, v65
	v_add_f32_e32 v172, v172, v66
	v_add_f32_e32 v173, v173, v67
	v_mfma_f32_32x32x16_bf16 v[0:15], v[252:255], v[230:233], v[0:15]
	ds_read_b64_tr_b16 v[252:253], v239 offset:19456
	ds_read_b64_tr_b16 v[254:255], v239 offset:19968
	v_add_f32_e32 v172, v172, v68
	v_add_f32_e32 v173, v173, v69
	v_add_f32_e32 v172, v172, v70
	v_add_f32_e32 v173, v173, v71
	v_mfma_f32_32x32x16_bf16 v[16:31], v[214:217], v[234:237], v[16:31]
	ds_read_b64_tr_b16 v[214:215], v239 offset:16384
	ds_read_b64_tr_b16 v[216:217], v239 offset:16896
	v_add_f32_e32 v172, v172, v72
	v_add_f32_e32 v173, v173, v73
	v_add_f32_e32 v172, v172, v74
	v_add_f32_e32 v173, v173, v75
	v_mfma_f32_32x32x16_bf16 v[0:15], v[218:221], v[234:237], v[0:15]
	ds_read_b64_tr_b16 v[218:219], v239 offset:20480
	ds_read_b64_tr_b16 v[220:221], v239 offset:20992
	v_add_f32_e32 v172, v172, v76
	v_add_f32_e32 v173, v173, v77
	v_add_f32_e32 v172, v172, v78
	v_add_f32_e32 v173, v173, v79
	s_waitcnt lgkmcnt(8)
	s_barrier
	v_mfma_f32_32x32x16_bf16 v[64:79], v[182:185], v[132:135], 0
	ds_read_b128 v[182:185], v238 offset:21504
	v_exp_f32_e32 v80, v80
	v_exp_f32_e32 v81, v81
	v_exp_f32_e32 v82, v82
	v_exp_f32_e32 v83, v83
	v_mfma_f32_32x32x16_bf16 v[64:79], v[186:189], v[136:139], v[64:79]
	ds_read_b128 v[186:189], v238 offset:21536
	v_exp_f32_e32 v84, v84
	v_exp_f32_e32 v85, v85
	v_cvt_pk_bf16_f32 v222, v80, v81
	v_cvt_pk_bf16_f32 v223, v82, v83
	v_mfma_f32_32x32x16_bf16 v[64:79], v[190:193], v[140:143], v[64:79]
	ds_read_b128 v[190:193], v238 offset:21568
	v_exp_f32_e32 v86, v86
	v_exp_f32_e32 v87, v87
	v_exp_f32_e32 v88, v88
	v_cvt_pk_bf16_f32 v224, v84, v85
	v_mfma_f32_32x32x16_bf16 v[64:79], v[194:197], v[144:147], v[64:79]
	ds_read_b128 v[194:197], v238 offset:21600
	v_exp_f32_e32 v89, v89
	v_exp_f32_e32 v90, v90
	v_cvt_pk_bf16_f32 v225, v86, v87
	v_exp_f32_e32 v91, v91
	v_mfma_f32_32x32x16_bf16 v[64:79], v[198:201], v[148:151], v[64:79]
	ds_read_b128 v[198:201], v238 offset:21632
	v_exp_f32_e32 v92, v92
	v_exp_f32_e32 v93, v93
	v_cvt_pk_bf16_f32 v226, v88, v89
	v_cvt_pk_bf16_f32 v227, v90, v91
	v_mfma_f32_32x32x16_bf16 v[64:79], v[202:205], v[152:155], v[64:79]
	ds_read_b128 v[202:205], v238 offset:21664
	v_exp_f32_e32 v94, v94
	v_exp_f32_e32 v95, v95
	v_cvt_pk_bf16_f32 v228, v92, v93
	v_cvt_pk_bf16_f32 v229, v94, v95
	s_waitcnt lgkmcnt(6)
	v_mfma_f32_32x32x16_bf16 v[32:47], v[248:251], v[222:225], v[32:47]
	v_add_f32_e32 v170, v170, v80
	v_add_f32_e32 v171, v171, v81
	v_add_f32_e32 v170, v170, v82
	v_add_f32_e32 v171, v171, v83
	v_mfma_f32_32x32x16_bf16 v[48:63], v[252:255], v[222:225], v[48:63]
	v_add_f32_e32 v170, v170, v84
	v_add_f32_e32 v171, v171, v85
	v_add_f32_e32 v170, v170, v86
	v_add_f32_e32 v171, v171, v87
	v_mfma_f32_32x32x16_bf16 v[32:47], v[214:217], v[226:229], v[32:47]
	v_add_f32_e32 v170, v170, v88
	v_add_f32_e32 v171, v171, v89
	v_add_f32_e32 v170, v170, v90
	v_add_f32_e32 v171, v171, v91
	v_mfma_f32_32x32x16_bf16 v[48:63], v[218:221], v[226:229], v[48:63]
	v_add_f32_e32 v170, v170, v92
	v_add_f32_e32 v171, v171, v93
	v_add_f32_e32 v170, v170, v94
	v_add_f32_e32 v171, v171, v95
	s_waitcnt vmcnt(0)
	s_add_i32 s4, s4, 1
	s_cmp_lt_u32 s4, s39
	s_cbranch_scc0 .Lp11_drain
; template <int DQK>
; __device__ __forceinline__ void attn_unit64(LAS char* lds, const bf16x8 (&qa)[DQK / 16], const bf16x8 (&qb)[DQK / 16],
;                                             const bf16_t* Kg, int ldk, const bf16_t* Vg, int ldv, int t0, int t1, bf16_t* Oga, int ogb_off) {
;     ...
;         for (int kv = 0; kv < 2; ++kv) {
;             __builtin_amdgcn_iglp_opt(0);
;             f32x16 sa, sb;
; #pragma unroll
;             for (int i = 0; i < 16; ++i) { sa[i] = 0.f; sb[i] = 0.f; }
; #pragma unroll
;             for (int ds = 0; ds < DQK / 16; ++ds) {
;                 const bf16x8 kf = *(const LAS bf16x8*)(kb + kv * 32 * KP + ds * 32);
;                 sa = __builtin_amdgcn_mfma_f32_32x32x16_bf16(kf, qa[ds], sa, 0, 0, 0);
;                 sb = __builtin_amdgcn_mfma_f32_32x32x16_bf16(kf, qb[ds], sb, 0, 0, 0);
;             }
; #pragma unroll
;             for (int i = 0; i < 16; i += 2) { sa[i] = __builtin_amdgcn_exp2f(sa[i]); sa[i + 1] = __builtin_amdgcn_exp2f(sa[i + 1]); la0 += sa[i]; la1 += sa[i + 1];
;                                                sb[i] = __builtin_amdgcn_exp2f(sb[i]); sb[i + 1] = __builtin_amdgcn_exp2f(sb[i + 1]); lb0 += sb[i]; lb1 += sb[i + 1]; }
;             bf16x8 pa[2], pb[2]; pa[0] = pack8(sa, 0); pa[1] = pack8(sa, 1); pb[0] = pack8(sb, 0); pb[1] = pack8(sb, 1);
; #pragma unroll
;             for (int s2 = 0; s2 < 2; ++s2) {
;                 const int s = 2 * kv + s2;
;                 const s16x4 a0 = vtr(vb + (16 * s) * 64), a1 = vtr(vb + (16 * s + 8) * 64), c0 = vtr(vb + 4096 + (16 * s) * 64), c1 = vtr(vb + 4096 + (16 * s + 8) * 64);
;                 const bf16x8 va = (bf16x8){a0[0], a0[1], a0[2], a0[3], a1[0], a1[1], a1[2], a1[3]}, vc = (bf16x8){c0[0], c0[1], c0[2], c0[3], c1[0], c1[1], c1[2], c1[3]};
;                 oa0 = __builtin_amdgcn_mfma_f32_32x32x16_bf16(va, pa[s2], oa0, 0, 0, 0);
;                 oa1 = __builtin_amdgcn_mfma_f32_32x32x16_bf16(vc, pa[s2], oa1, 0, 0, 0);
;                 ob0 = __builtin_amdgcn_mfma_f32_32x32x16_bf16(va, pb[s2], ob0, 0, 0, 0);
;                 ob1 = __builtin_amdgcn_mfma_f32_32x32x16_bf16(vc, pb[s2], ob1, 0, 0, 0);
;             }
;         }
;         if (more) { const unsigned bo = (cur ^ 1) * BUF; *(LAS u32x4*)(lds + bo + kdst0) = kreg0; if (k2) *(LAS u32x4*)(lds + bo + kdst1) = kreg1; *(LAS u32x4*)(lds + bo + vdst) = vreg; }
	s_waitcnt lgkmcnt(0)
	v_mfma_f32_32x32x16_bf16 v[80:95], v[182:185], v[128:131], 0
	v_exp_f32_e32 v64, v64
	v_exp_f32_e32 v65, v65
	v_exp_f32_e32 v66, v66
	v_exp_f32_e32 v67, v67
	v_mfma_f32_32x32x16_bf16 v[80:95], v[186:189], v[124:127], v[80:95]
	v_exp_f32_e32 v68, v68
	v_exp_f32_e32 v69, v69
	v_cvt_pk_bf16_f32 v230, v64, v65
	v_cvt_pk_bf16_f32 v231, v66, v67
	v_mfma_f32_32x32x16_bf16 v[80:95], v[190:193], v[120:123], v[80:95]
	v_exp_f32_e32 v70, v70
	v_exp_f32_e32 v71, v71
	v_exp_f32_e32 v72, v72
	v_cvt_pk_bf16_f32 v232, v68, v69
	v_mfma_f32_32x32x16_bf16 v[80:95], v[194:197], v[116:119], v[80:95]
	v_exp_f32_e32 v73, v73
	v_exp_f32_e32 v74, v74
	v_cvt_pk_bf16_f32 v233, v70, v71
	v_exp_f32_e32 v75, v75
	v_mfma_f32_32x32x16_bf16 v[80:95], v[198:201], v[108:111], v[80:95]
	v_exp_f32_e32 v76, v76
	v_exp_f32_e32 v77, v77
	v_cvt_pk_bf16_f32 v234, v72, v73
	v_cvt_pk_bf16_f32 v235, v74, v75
	v_mfma_f32_32x32x16_bf16 v[80:95], v[202:205], v[112:115], v[80:95]
	v_exp_f32_e32 v78, v78
	v_exp_f32_e32 v79, v79
	v_cvt_pk_bf16_f32 v236, v76, v77
	v_cvt_pk_bf16_f32 v237, v78, v79
	v_mfma_f32_32x32x16_bf16 v[16:31], v[248:251], v[230:233], v[16:31]
	ds_read_b64_tr_b16 v[248:249], v239 offset:34816
	ds_read_b64_tr_b16 v[250:251], v239 offset:35328
	v_add_f32_e32 v172, v172, v64
	v_add_f32_e32 v173, v173, v65
	v_add_f32_e32 v172, v172, v66
	v_add_f32_e32 v173, v173, v67
	v_mfma_f32_32x32x16_bf16 v[0:15], v[252:255], v[230:233], v[0:15]
	ds_read_b64_tr_b16 v[252:253], v239 offset:38912
	ds_read_b64_tr_b16 v[254:255], v239 offset:39424
	v_add_f32_e32 v172, v172, v68
	v_add_f32_e32 v173, v173, v69
	v_add_f32_e32 v172, v172, v70
	v_add_f32_e32 v173, v173, v71
	v_mfma_f32_32x32x16_bf16 v[16:31], v[214:217], v[234:237], v[16:31]
	ds_read_b64_tr_b16 v[214:215], v239 offset:35840
	ds_read_b64_tr_b16 v[216:217], v239 offset:36352
	v_add_f32_e32 v172, v172, v72
	v_add_f32_e32 v173, v173, v73
	v_add_f32_e32 v172, v172, v74
	v_add_f32_e32 v173, v173, v75
	v_mfma_f32_32x32x16_bf16 v[0:15], v[218:221], v[234:237], v[0:15]
	ds_read_b64_tr_b16 v[218:219], v239 offset:39936
	ds_read_b64_tr_b16 v[220:221], v239 offset:40448
	v_add_f32_e32 v172, v172, v76
	v_add_f32_e32 v173, v173, v77
	v_add_f32_e32 v172, v172, v78
	v_add_f32_e32 v173, v173, v79
	v_mfma_f32_32x32x16_bf16 v[64:79], v[182:185], v[132:135], 0
	ds_read_b128 v[182:185], v238 offset:28160
	v_exp_f32_e32 v80, v80
	v_exp_f32_e32 v81, v81
	v_exp_f32_e32 v82, v82
	v_exp_f32_e32 v83, v83
	v_mfma_f32_32x32x16_bf16 v[64:79], v[186:189], v[136:139], v[64:79]
	ds_read_b128 v[186:189], v238 offset:28192
	v_exp_f32_e32 v84, v84
	v_exp_f32_e32 v85, v85
	v_cvt_pk_bf16_f32 v222, v80, v81
	v_cvt_pk_bf16_f32 v223, v82, v83
	v_mfma_f32_32x32x16_bf16 v[64:79], v[190:193], v[140:143], v[64:79]
	ds_read_b128 v[190:193], v238 offset:28224
	v_exp_f32_e32 v86, v86
	v_exp_f32_e32 v87, v87
	v_exp_f32_e32 v88, v88
	v_cvt_pk_bf16_f32 v224, v84, v85
	v_mfma_f32_32x32x16_bf16 v[64:79], v[194:197], v[144:147], v[64:79]
	ds_read_b128 v[194:197], v238 offset:28256
	v_exp_f32_e32 v89, v89
	v_exp_f32_e32 v90, v90
	v_cvt_pk_bf16_f32 v225, v86, v87
	v_exp_f32_e32 v91, v91
	v_mfma_f32_32x32x16_bf16 v[64:79], v[198:201], v[148:151], v[64:79]
	ds_read_b128 v[198:201], v238 offset:28288
	v_exp_f32_e32 v92, v92
	v_exp_f32_e32 v93, v93
	v_cvt_pk_bf16_f32 v226, v88, v89
	v_cvt_pk_bf16_f32 v227, v90, v91
	v_mfma_f32_32x32x16_bf16 v[64:79], v[202:205], v[152:155], v[64:79]
	ds_read_b128 v[202:205], v238 offset:28320
	v_exp_f32_e32 v94, v94
	v_exp_f32_e32 v95, v95
	v_cvt_pk_bf16_f32 v228, v92, v93
	v_cvt_pk_bf16_f32 v229, v94, v95
	s_waitcnt lgkmcnt(6)
	v_mfma_f32_32x32x16_bf16 v[32:47], v[248:251], v[222:225], v[32:47]
	v_add_f32_e32 v170, v170, v80
	v_add_f32_e32 v171, v171, v81
	v_add_f32_e32 v170, v170, v82
	v_add_f32_e32 v171, v171, v83
	s_waitcnt vmcnt(0)
	ds_write_b128 v159, v[96:99] offset:43008
	s_cmp_eq_u64 s[0:1], 0
	v_mfma_f32_32x32x16_bf16 v[48:63], v[252:255], v[222:225], v[48:63]
	v_add_f32_e32 v170, v170, v84
	v_add_f32_e32 v171, v171, v85
	v_add_f32_e32 v170, v170, v86
	v_add_f32_e32 v171, v171, v87
	s_cbranch_scc1 .Lp11_w1_a1
	ds_write_b128 v212, v[100:103] offset:43008

; template <int DQK>
; __device__ __forceinline__ void attn_unit64(LAS char* lds, const bf16x8 (&qa)[DQK / 16], const bf16x8 (&qb)[DQK / 16],
;                                             const bf16_t* Kg, int ldk, const bf16_t* Vg, int ldv, int t0, int t1, bf16_t* Oga, int ogb_off) {
;     ...
;         for (int kv = 0; kv < 2; ++kv) {
;             __builtin_amdgcn_iglp_opt(0);
;             f32x16 sa, sb;
; #pragma unroll
;             for (int i = 0; i < 16; ++i) { sa[i] = 0.f; sb[i] = 0.f; }
; #pragma unroll
;             for (int ds = 0; ds < DQK / 16; ++ds) {
;                 const bf16x8 kf = *(const LAS bf16x8*)(kb + kv * 32 * KP + ds * 32);
;                 sa = __builtin_amdgcn_mfma_f32_32x32x16_bf16(kf, qa[ds], sa, 0, 0, 0);
;                 sb = __builtin_amdgcn_mfma_f32_32x32x16_bf16(kf, qb[ds], sb, 0, 0, 0);
;             }
; #pragma unroll
;             for (int i = 0; i < 16; i += 2) { sa[i] = __builtin_amdgcn_exp2f(sa[i]); sa[i + 1] = __builtin_amdgcn_exp2f(sa[i + 1]); la0 += sa[i]; la1 += sa[i + 1];
;                                                sb[i] = __builtin_amdgcn_exp2f(sb[i]); sb[i + 1] = __builtin_amdgcn_exp2f(sb[i + 1]); lb0 += sb[i]; lb1 += sb[i + 1]; }
;             bf16x8 pa[2], pb[2]; pa[0] = pack8(sa, 0); pa[1] = pack8(sa, 1); pb[0] = pack8(sb, 0); pb[1] = pack8(sb, 1);
; #pragma unroll
;             for (int s2 = 0; s2 < 2; ++s2) {
;                 const int s = 2 * kv + s2;
;                 const s16x4 a0 = vtr(vb + (16 * s) * 64), a1 = vtr(vb + (16 * s + 8) * 64), c0 = vtr(vb + 4096 + (16 * s) * 64), c1 = vtr(vb + 4096 + (16 * s + 8) * 64);
;                 const bf16x8 va = (bf16x8){a0[0], a0[1], a0[2], a0[3], a1[0], a1[1], a1[2], a1[3]}, vc = (bf16x8){c0[0], c0[1], c0[2], c0[3], c1[0], c1[1], c1[2], c1[3]};
;                 oa0 = __builtin_amdgcn_mfma_f32_32x32x16_bf16(va, pa[s2], oa0, 0, 0, 0);
;                 oa1 = __builtin_amdgcn_mfma_f32_32x32x16_bf16(vc, pa[s2], oa1, 0, 0, 0);
;                 ob0 = __builtin_amdgcn_mfma_f32_32x32x16_bf16(va, pb[s2], ob0, 0, 0, 0);
;                 ob1 = __builtin_amdgcn_mfma_f32_32x32x16_bf16(vc, pb[s2], ob1, 0, 0, 0);
;             }
;         }
;         if (more) { const unsigned bo = (cur ^ 1) * BUF; *(LAS u32x4*)(lds + bo + kdst0) = kreg0; if (k2) *(LAS u32x4*)(lds + bo + kdst1) = kreg1; *(LAS u32x4*)(lds + bo + vdst) = vreg; }
;         __syncthreads();
.Lp11_g1_a1:
	global_load_dwordx4 v[104:107], v[180:181], off
	s_waitcnt lgkmcnt(2)
	v_mfma_f32_32x32x16_bf16 v[80:95], v[182:185], v[128:131], 0
	v_exp_f32_e32 v64, v64
	v_exp_f32_e32 v65, v65
	v_exp_f32_e32 v66, v66
	v_exp_f32_e32 v67, v67
	v_mfma_f32_32x32x16_bf16 v[80:95], v[186:189], v[124:127], v[80:95]
	v_exp_f32_e32 v68, v68
	v_exp_f32_e32 v69, v69
	v_cvt_pk_bf16_f32 v230, v64, v65
	v_cvt_pk_bf16_f32 v231, v66, v67
	v_mfma_f32_32x32x16_bf16 v[80:95], v[190:193], v[120:123], v[80:95]
	v_exp_f32_e32 v70, v70
	v_exp_f32_e32 v71, v71
	v_exp_f32_e32 v72, v72
	v_cvt_pk_bf16_f32 v232, v68, v69
	v_mfma_f32_32x32x16_bf16 v[80:95], v[194:197], v[116:119], v[80:95]
	v_exp_f32_e32 v73, v73
	v_exp_f32_e32 v74, v74
	v_cvt_pk_bf16_f32 v233, v70, v71
	v_exp_f32_e32 v75, v75
	v_mfma_f32_32x32x16_bf16 v[80:95], v[198:201], v[108:111], v[80:95]
	v_exp_f32_e32 v76, v76
	v_exp_f32_e32 v77, v77
	v_cvt_pk_bf16_f32 v234, v72, v73
	v_cvt_pk_bf16_f32 v235, v74, v75
	v_mfma_f32_32x32x16_bf16 v[80:95], v[202:205], v[112:115], v[80:95]
	v_exp_f32_e32 v78, v78
	v_exp_f32_e32 v79, v79
	v_cvt_pk_bf16_f32 v236, v76, v77
	v_cvt_pk_bf16_f32 v237, v78, v79
	v_mfma_f32_32x32x16_bf16 v[16:31], v[248:251], v[230:233], v[16:31]
	ds_read_b64_tr_b16 v[248:249], v239 offset:36864
	ds_read_b64_tr_b16 v[250:251], v239 offset:37376
	v_add_f32_e32 v172, v172, v64
	v_add_f32_e32 v173, v173, v65
	v_add_f32_e32 v172, v172, v66
	v_add_f32_e32 v173, v173, v67
	v_mfma_f32_32x32x16_bf16 v[0:15], v[252:255], v[230:233], v[0:15]
	ds_read_b64_tr_b16 v[252:253], v239 offset:40960
	ds_read_b64_tr_b16 v[254:255], v239 offset:41472
	v_add_f32_e32 v172, v172, v68
	v_add_f32_e32 v173, v173, v69
	v_add_f32_e32 v172, v172, v70
	v_add_f32_e32 v173, v173, v71
	v_mfma_f32_32x32x16_bf16 v[16:31], v[214:217], v[234:237], v[16:31]
	ds_read_b64_tr_b16 v[214:215], v239 offset:37888
	ds_read_b64_tr_b16 v[216:217], v239 offset:38400
	v_add_f32_e32 v172, v172, v72
	v_add_f32_e32 v173, v173, v73
	v_add_f32_e32 v172, v172, v74
	v_add_f32_e32 v173, v173, v75
	v_mfma_f32_32x32x16_bf16 v[0:15], v[218:221], v[234:237], v[0:15]
	ds_read_b64_tr_b16 v[218:219], v239 offset:41984
	ds_read_b64_tr_b16 v[220:221], v239 offset:42496
	v_add_f32_e32 v172, v172, v76
	v_add_f32_e32 v173, v173, v77
	v_add_f32_e32 v172, v172, v78
	v_add_f32_e32 v173, v173, v79
	s_waitcnt lgkmcnt(8)
	s_barrier
	v_mfma_f32_32x32x16_bf16 v[64:79], v[182:185], v[132:135], 0
	ds_read_b128 v[182:185], v238 offset:43008
	v_exp_f32_e32 v80, v80
	v_exp_f32_e32 v81, v81
	v_exp_f32_e32 v82, v82
	v_exp_f32_e32 v83, v83
	v_mfma_f32_32x32x16_bf16 v[64:79], v[186:189], v[136:139], v[64:79]
	ds_read_b128 v[186:189], v238 offset:43040
	v_exp_f32_e32 v84, v84
	v_exp_f32_e32 v85, v85
	v_cvt_pk_bf16_f32 v222, v80, v81
	v_cvt_pk_bf16_f32 v223, v82, v83
	v_mfma_f32_32x32x16_bf16 v[64:79], v[190:193], v[140:143], v[64:79]
	ds_read_b128 v[190:193], v238 offset:43072
	v_exp_f32_e32 v86, v86
	v_exp_f32_e32 v87, v87
	v_exp_f32_e32 v88, v88
	v_cvt_pk_bf16_f32 v224, v84, v85
	v_mfma_f32_32x32x16_bf16 v[64:79], v[194:197], v[144:147], v[64:79]
	ds_read_b128 v[194:197], v238 offset:43104
	v_exp_f32_e32 v89, v89
	v_exp_f32_e32 v90, v90
	v_cvt_pk_bf16_f32 v225, v86, v87
	v_exp_f32_e32 v91, v91
	v_mfma_f32_32x32x16_bf16 v[64:79], v[198:201], v[148:151], v[64:79]
	ds_read_b128 v[198:201], v238 offset:43136
	v_exp_f32_e32 v92, v92
	v_exp_f32_e32 v93, v93
	v_cvt_pk_bf16_f32 v226, v88, v89
	v_cvt_pk_bf16_f32 v227, v90, v91
	v_mfma_f32_32x32x16_bf16 v[64:79], v[202:205], v[152:155], v[64:79]
	ds_read_b128 v[202:205], v238 offset:43168
	v_exp_f32_e32 v94, v94
	v_exp_f32_e32 v95, v95
	v_cvt_pk_bf16_f32 v228, v92, v93
	v_cvt_pk_bf16_f32 v229, v94, v95
	s_waitcnt lgkmcnt(6)
	v_mfma_f32_32x32x16_bf16 v[32:47], v[248:251], v[222:225], v[32:47]
	v_add_f32_e32 v170, v170, v80
	v_add_f32_e32 v171, v171, v81
	v_add_f32_e32 v170, v170, v82
	v_add_f32_e32 v171, v171, v83
	v_mfma_f32_32x32x16_bf16 v[48:63], v[252:255], v[222:225], v[48:63]
	v_add_f32_e32 v170, v170, v84
	v_add_f32_e32 v171, v171, v85
	v_add_f32_e32 v170, v170, v86
	v_add_f32_e32 v171, v171, v87
	v_mfma_f32_32x32x16_bf16 v[32:47], v[214:217], v[226:229], v[32:47]
	v_add_f32_e32 v170, v170, v88
	v_add_f32_e32 v171, v171, v89
	v_add_f32_e32 v170, v170, v90
	v_add_f32_e32 v171, v171, v91
	v_mfma_f32_32x32x16_bf16 v[48:63], v[218:221], v[226:229], v[48:63]
	v_add_f32_e32 v170, v170, v92
	v_add_f32_e32 v171, v171, v93
	v_add_f32_e32 v170, v170, v94
	v_add_f32_e32 v171, v171, v95
	s_waitcnt vmcnt(0)
	s_add_i32 s4, s4, 1
	s_cmp_lt_u32 s4, s39
	s_cbranch_scc0 .Lp11_drain
; template <int DQK>
; __device__ __forceinline__ void attn_unit64(LAS char* lds, const bf16x8 (&qa)[DQK / 16], const bf16x8 (&qb)[DQK / 16],
;                                             const bf16_t* Kg, int ldk, const bf16_t* Vg, int ldv, int t0, int t1, bf16_t* Oga, int ogb_off) {
;     ...
;         for (int kv = 0; kv < 2; ++kv) {
;             __builtin_amdgcn_iglp_opt(0);
;             f32x16 sa, sb;
; #pragma unroll
;             for (int i = 0; i < 16; ++i) { sa[i] = 0.f; sb[i] = 0.f; }
; #pragma unroll
;             for (int ds = 0; ds < DQK / 16; ++ds) {
;                 const bf16x8 kf = *(const LAS bf16x8*)(kb + kv * 32 * KP + ds * 32);
;                 sa = __builtin_amdgcn_mfma_f32_32x32x16_bf16(kf, qa[ds], sa, 0, 0, 0);
;                 sb = __builtin_amdgcn_mfma_f32_32x32x16_bf16(kf, qb[ds], sb, 0, 0, 0);
;             }
; #pragma unroll
;             for (int i = 0; i < 16; i += 2) { sa[i] = __builtin_amdgcn_exp2f(sa[i]); sa[i + 1] = __builtin_amdgcn_exp2f(sa[i + 1]); la0 += sa[i]; la1 += sa[i + 1];
;                                                sb[i] = __builtin_amdgcn_exp2f(sb[i]); sb[i + 1] = __builtin_amdgcn_exp2f(sb[i + 1]); lb0 += sb[i]; lb1 += sb[i + 1]; }
;             bf16x8 pa[2], pb[2]; pa[0] = pack8(sa, 0); pa[1] = pack8(sa, 1); pb[0] = pack8(sb, 0); pb[1] = pack8(sb, 1);
; #pragma unroll
;             for (int s2 = 0; s2 < 2; ++s2) {
;                 const int s = 2 * kv + s2;
;                 const s16x4 a0 = vtr(vb + (16 * s) * 64), a1 = vtr(vb + (16 * s + 8) * 64), c0 = vtr(vb + 4096 + (16 * s) * 64), c1 = vtr(vb + 4096 + (16 * s + 8) * 64);
;                 const bf16x8 va = (bf16x8){a0[0], a0[1], a0[2], a0[3], a1[0], a1[1], a1[2], a1[3]}, vc = (bf16x8){c0[0], c0[1], c0[2], c0[3], c1[0], c1[1], c1[2], c1[3]};
;                 oa0 = __builtin_amdgcn_mfma_f32_32x32x16_bf16(va, pa[s2], oa0, 0, 0, 0);
;                 oa1 = __builtin_amdgcn_mfma_f32_32x32x16_bf16(vc, pa[s2], oa1, 0, 0, 0);
;                 ob0 = __builtin_amdgcn_mfma_f32_32x32x16_bf16(va, pb[s2], ob0, 0, 0, 0);
;                 ob1 = __builtin_amdgcn_mfma_f32_32x32x16_bf16(vc, pb[s2], ob1, 0, 0, 0);
;             }
;         }
;         if (more) { const unsigned bo = (cur ^ 1) * BUF; *(LAS u32x4*)(lds + bo + kdst0) = kreg0; if (k2) *(LAS u32x4*)(lds + bo + kdst1) = kreg1; *(LAS u32x4*)(lds + bo + vdst) = vreg; }
	s_waitcnt lgkmcnt(0)
	v_mfma_f32_32x32x16_bf16 v[80:95], v[182:185], v[128:131], 0
	v_exp_f32_e32 v64, v64
	v_exp_f32_e32 v65, v65
	v_exp_f32_e32 v66, v66
	v_exp_f32_e32 v67, v67
	v_mfma_f32_32x32x16_bf16 v[80:95], v[186:189], v[124:127], v[80:95]
	v_exp_f32_e32 v68, v68
	v_exp_f32_e32 v69, v69
	v_cvt_pk_bf16_f32 v230, v64, v65
	v_cvt_pk_bf16_f32 v231, v66, v67
	v_mfma_f32_32x32x16_bf16 v[80:95], v[190:193], v[120:123], v[80:95]
	v_exp_f32_e32 v70, v70
	v_exp_f32_e32 v71, v71
	v_exp_f32_e32 v72, v72
	v_cvt_pk_bf16_f32 v232, v68, v69
	v_mfma_f32_32x32x16_bf16 v[80:95], v[194:197], v[116:119], v[80:95]
	v_exp_f32_e32 v73, v73
	v_exp_f32_e32 v74, v74
	v_cvt_pk_bf16_f32 v233, v70, v71
	v_exp_f32_e32 v75, v75
	v_mfma_f32_32x32x16_bf16 v[80:95], v[198:201], v[108:111], v[80:95]
	v_exp_f32_e32 v76, v76
	v_exp_f32_e32 v77, v77
	v_cvt_pk_bf16_f32 v234, v72, v73
	v_cvt_pk_bf16_f32 v235, v74, v75
	v_mfma_f32_32x32x16_bf16 v[80:95], v[202:205], v[112:115], v[80:95]
	v_exp_f32_e32 v78, v78
	v_exp_f32_e32 v79, v79
	v_cvt_pk_bf16_f32 v236, v76, v77
	v_cvt_pk_bf16_f32 v237, v78, v79
	v_mfma_f32_32x32x16_bf16 v[16:31], v[248:251], v[230:233], v[16:31]
	ds_read_b64_tr_b16 v[248:249], v239 offset:56320
	ds_read_b64_tr_b16 v[250:251], v239 offset:56832
	v_add_f32_e32 v172, v172, v64
	v_add_f32_e32 v173, v173, v65
	v_add_f32_e32 v172, v172, v66
	v_add_f32_e32 v173, v173, v67
	v_mfma_f32_32x32x16_bf16 v[0:15], v[252:255], v[230:233], v[0:15]
	ds_read_b64_tr_b16 v[252:253], v239 offset:60416
	ds_read_b64_tr_b16 v[254:255], v239 offset:60928
	v_add_f32_e32 v172, v172, v68
	v_add_f32_e32 v173, v173, v69
	v_add_f32_e32 v172, v172, v70
	v_add_f32_e32 v173, v173, v71
	v_mfma_f32_32x32x16_bf16 v[16:31], v[214:217], v[234:237], v[16:31]
	ds_read_b64_tr_b16 v[214:215], v239 offset:57344
	ds_read_b64_tr_b16 v[216:217], v239 offset:57856
	v_add_f32_e32 v172, v172, v72
	v_add_f32_e32 v173, v173, v73
	v_add_f32_e32 v172, v172, v74
	v_add_f32_e32 v173, v173, v75
	v_mfma_f32_32x32x16_bf16 v[0:15], v[218:221], v[234:237], v[0:15]
	ds_read_b64_tr_b16 v[218:219], v239 offset:61440
	ds_read_b64_tr_b16 v[220:221], v239 offset:61952
	v_add_f32_e32 v172, v172, v76
	v_add_f32_e32 v173, v173, v77
	v_add_f32_e32 v172, v172, v78
	v_add_f32_e32 v173, v173, v79
	v_mfma_f32_32x32x16_bf16 v[64:79], v[182:185], v[132:135], 0
	ds_read_b128 v[182:185], v238 offset:49664
	v_exp_f32_e32 v80, v80
	v_exp_f32_e32 v81, v81
	v_exp_f32_e32 v82, v82
	v_exp_f32_e32 v83, v83
	v_mfma_f32_32x32x16_bf16 v[64:79], v[186:189], v[136:139], v[64:79]
	ds_read_b128 v[186:189], v238 offset:49696
	v_exp_f32_e32 v84, v84
	v_exp_f32_e32 v85, v85
	v_cvt_pk_bf16_f32 v222, v80, v81
	v_cvt_pk_bf16_f32 v223, v82, v83
	v_mfma_f32_32x32x16_bf16 v[64:79], v[190:193], v[140:143], v[64:79]
	ds_read_b128 v[190:193], v238 offset:49728
	v_exp_f32_e32 v86, v86
	v_exp_f32_e32 v87, v87
	v_exp_f32_e32 v88, v88
	v_cvt_pk_bf16_f32 v224, v84, v85
	v_mfma_f32_32x32x16_bf16 v[64:79], v[194:197], v[144:147], v[64:79]
	ds_read_b128 v[194:197], v238 offset:49760
	v_exp_f32_e32 v89, v89
	v_exp_f32_e32 v90, v90
	v_cvt_pk_bf16_f32 v225, v86, v87
	v_exp_f32_e32 v91, v91
	v_mfma_f32_32x32x16_bf16 v[64:79], v[198:201], v[148:151], v[64:79]
	ds_read_b128 v[198:201], v238 offset:49792
	v_exp_f32_e32 v92, v92
	v_exp_f32_e32 v93, v93
	v_cvt_pk_bf16_f32 v226, v88, v89
	v_cvt_pk_bf16_f32 v227, v90, v91
	v_mfma_f32_32x32x16_bf16 v[64:79], v[202:205], v[152:155], v[64:79]
	ds_read_b128 v[202:205], v238 offset:49824
	v_exp_f32_e32 v94, v94
	v_exp_f32_e32 v95, v95
	v_cvt_pk_bf16_f32 v228, v92, v93
	v_cvt_pk_bf16_f32 v229, v94, v95
	s_waitcnt lgkmcnt(6)
	v_mfma_f32_32x32x16_bf16 v[32:47], v[248:251], v[222:225], v[32:47]
	v_add_f32_e32 v170, v170, v80
	v_add_f32_e32 v171, v171, v81
	v_add_f32_e32 v170, v170, v82
	v_add_f32_e32 v171, v171, v83
	s_waitcnt vmcnt(0)
	ds_write_b128 v159, v[96:99] offset:0
	s_cmp_eq_u64 s[0:1], 0
	v_mfma_f32_32x32x16_bf16 v[48:63], v[252:255], v[222:225], v[48:63]
	v_add_f32_e32 v170, v170, v84
	v_add_f32_e32 v171, v171, v85
	v_add_f32_e32 v170, v170, v86
	v_add_f32_e32 v171, v171, v87
	s_cbranch_scc1 .Lp11_w1_a2
	ds_write_b128 v212, v[100:103] offset:0

; template <int DQK>
; __device__ __forceinline__ void attn_unit64(LAS char* lds, const bf16x8 (&qa)[DQK / 16], const bf16x8 (&qb)[DQK / 16],
;                                             const bf16_t* Kg, int ldk, const bf16_t* Vg, int ldv, int t0, int t1, bf16_t* Oga, int ogb_off) {
;     ...
;         for (int kv = 0; kv < 2; ++kv) {
;             __builtin_amdgcn_iglp_opt(0);
;             f32x16 sa, sb;
; #pragma unroll
;             for (int i = 0; i < 16; ++i) { sa[i] = 0.f; sb[i] = 0.f; }
; #pragma unroll
;             for (int ds = 0; ds < DQK / 16; ++ds) {
;                 const bf16x8 kf = *(const LAS bf16x8*)(kb + kv * 32 * KP + ds * 32);
;                 sa = __builtin_amdgcn_mfma_f32_32x32x16_bf16(kf, qa[ds], sa, 0, 0, 0);
;                 sb = __builtin_amdgcn_mfma_f32_32x32x16_bf16(kf, qb[ds], sb, 0, 0, 0);
;             }
; #pragma unroll
;             for (int i = 0; i < 16; i += 2) { sa[i] = __builtin_amdgcn_exp2f(sa[i]); sa[i + 1] = __builtin_amdgcn_exp2f(sa[i + 1]); la0 += sa[i]; la1 += sa[i + 1];
;                                                sb[i] = __builtin_amdgcn_exp2f(sb[i]); sb[i + 1] = __builtin_amdgcn_exp2f(sb[i + 1]); lb0 += sb[i]; lb1 += sb[i + 1]; }
;             bf16x8 pa[2], pb[2]; pa[0] = pack8(sa, 0); pa[1] = pack8(sa, 1); pb[0] = pack8(sb, 0); pb[1] = pack8(sb, 1);
; #pragma unroll
;             for (int s2 = 0; s2 < 2; ++s2) {
;                 const int s = 2 * kv + s2;
;                 const s16x4 a0 = vtr(vb + (16 * s) * 64), a1 = vtr(vb + (16 * s + 8) * 64), c0 = vtr(vb + 4096 + (16 * s) * 64), c1 = vtr(vb + 4096 + (16 * s + 8) * 64);
;                 const bf16x8 va = (bf16x8){a0[0], a0[1], a0[2], a0[3], a1[0], a1[1], a1[2], a1[3]}, vc = (bf16x8){c0[0], c0[1], c0[2], c0[3], c1[0], c1[1], c1[2], c1[3]};
;                 oa0 = __builtin_amdgcn_mfma_f32_32x32x16_bf16(va, pa[s2], oa0, 0, 0, 0);
;                 oa1 = __builtin_amdgcn_mfma_f32_32x32x16_bf16(vc, pa[s2], oa1, 0, 0, 0);
;                 ob0 = __builtin_amdgcn_mfma_f32_32x32x16_bf16(va, pb[s2], ob0, 0, 0, 0);
;                 ob1 = __builtin_amdgcn_mfma_f32_32x32x16_bf16(vc, pb[s2], ob1, 0, 0, 0);
;             }
;         }
;         if (more) { const unsigned bo = (cur ^ 1) * BUF; *(LAS u32x4*)(lds + bo + kdst0) = kreg0; if (k2) *(LAS u32x4*)(lds + bo + kdst1) = kreg1; *(LAS u32x4*)(lds + bo + vdst) = vreg; }
;         __syncthreads();
.Lp11_g1_a2:
	global_load_dwordx4 v[104:107], v[180:181], off
	s_waitcnt lgkmcnt(2)
	v_mfma_f32_32x32x16_bf16 v[80:95], v[182:185], v[128:131], 0
	v_exp_f32_e32 v64, v64
	v_exp_f32_e32 v65, v65
	v_exp_f32_e32 v66, v66
	v_exp_f32_e32 v67, v67
	v_mfma_f32_32x32x16_bf16 v[80:95], v[186:189], v[124:127], v[80:95]
	v_exp_f32_e32 v68, v68
	v_exp_f32_e32 v69, v69
	v_cvt_pk_bf16_f32 v230, v64, v65
	v_cvt_pk_bf16_f32 v231, v66, v67
	v_mfma_f32_32x32x16_bf16 v[80:95], v[190:193], v[120:123], v[80:95]
	v_exp_f32_e32 v70, v70
	v_exp_f32_e32 v71, v71
	v_exp_f32_e32 v72, v72
	v_cvt_pk_bf16_f32 v232, v68, v69
	v_mfma_f32_32x32x16_bf16 v[80:95], v[194:197], v[116:119], v[80:95]
	v_exp_f32_e32 v73, v73
	v_exp_f32_e32 v74, v74
	v_cvt_pk_bf16_f32 v233, v70, v71
	v_exp_f32_e32 v75, v75
	v_mfma_f32_32x32x16_bf16 v[80:95], v[198:201], v[108:111], v[80:95]
	v_exp_f32_e32 v76, v76
	v_exp_f32_e32 v77, v77
	v_cvt_pk_bf16_f32 v234, v72, v73
	v_cvt_pk_bf16_f32 v235, v74, v75
	v_mfma_f32_32x32x16_bf16 v[80:95], v[202:205], v[112:115], v[80:95]
	v_exp_f32_e32 v78, v78
	v_exp_f32_e32 v79, v79
	v_cvt_pk_bf16_f32 v236, v76, v77
	v_cvt_pk_bf16_f32 v237, v78, v79
	v_mfma_f32_32x32x16_bf16 v[16:31], v[248:251], v[230:233], v[16:31]
	ds_read_b64_tr_b16 v[248:249], v239 offset:58368
	ds_read_b64_tr_b16 v[250:251], v239 offset:58880
	v_add_f32_e32 v172, v172, v64
	v_add_f32_e32 v173, v173, v65
	v_add_f32_e32 v172, v172, v66
	v_add_f32_e32 v173, v173, v67
	v_mfma_f32_32x32x16_bf16 v[0:15], v[252:255], v[230:233], v[0:15]
	ds_read_b64_tr_b16 v[252:253], v239 offset:62464
	ds_read_b64_tr_b16 v[254:255], v239 offset:62976
	v_add_f32_e32 v172, v172, v68
	v_add_f32_e32 v173, v173, v69
	v_add_f32_e32 v172, v172, v70
	v_add_f32_e32 v173, v173, v71
	v_mfma_f32_32x32x16_bf16 v[16:31], v[214:217], v[234:237], v[16:31]
	ds_read_b64_tr_b16 v[214:215], v239 offset:59392
	ds_read_b64_tr_b16 v[216:217], v239 offset:59904
	v_add_f32_e32 v172, v172, v72
	v_add_f32_e32 v173, v173, v73
	v_add_f32_e32 v172, v172, v74
	v_add_f32_e32 v173, v173, v75
	v_mfma_f32_32x32x16_bf16 v[0:15], v[218:221], v[234:237], v[0:15]
	ds_read_b64_tr_b16 v[218:219], v239 offset:63488
	ds_read_b64_tr_b16 v[220:221], v239 offset:64000
	v_add_f32_e32 v172, v172, v76
	v_add_f32_e32 v173, v173, v77
	v_add_f32_e32 v172, v172, v78
	v_add_f32_e32 v173, v173, v79
	s_waitcnt lgkmcnt(8)
	s_barrier
	v_mfma_f32_32x32x16_bf16 v[64:79], v[182:185], v[132:135], 0
	ds_read_b128 v[182:185], v238
	v_exp_f32_e32 v80, v80
	v_exp_f32_e32 v81, v81
	v_exp_f32_e32 v82, v82
	v_exp_f32_e32 v83, v83
	v_mfma_f32_32x32x16_bf16 v[64:79], v[186:189], v[136:139], v[64:79]
	ds_read_b128 v[186:189], v238 offset:32
	v_exp_f32_e32 v84, v84
	v_exp_f32_e32 v85, v85
	v_cvt_pk_bf16_f32 v222, v80, v81
	v_cvt_pk_bf16_f32 v223, v82, v83
	v_mfma_f32_32x32x16_bf16 v[64:79], v[190:193], v[140:143], v[64:79]
	ds_read_b128 v[190:193], v238 offset:64
	v_exp_f32_e32 v86, v86
	v_exp_f32_e32 v87, v87
	v_exp_f32_e32 v88, v88
	v_cvt_pk_bf16_f32 v224, v84, v85
	v_mfma_f32_32x32x16_bf16 v[64:79], v[194:197], v[144:147], v[64:79]
	ds_read_b128 v[194:197], v238 offset:96
	v_exp_f32_e32 v89, v89
	v_exp_f32_e32 v90, v90
	v_cvt_pk_bf16_f32 v225, v86, v87
	v_exp_f32_e32 v91, v91
	v_mfma_f32_32x32x16_bf16 v[64:79], v[198:201], v[148:151], v[64:79]
	ds_read_b128 v[198:201], v238 offset:128
	v_exp_f32_e32 v92, v92
	v_exp_f32_e32 v93, v93
	v_cvt_pk_bf16_f32 v226, v88, v89
	v_cvt_pk_bf16_f32 v227, v90, v91
	v_mfma_f32_32x32x16_bf16 v[64:79], v[202:205], v[152:155], v[64:79]
	ds_read_b128 v[202:205], v238 offset:160
	v_exp_f32_e32 v94, v94
	v_exp_f32_e32 v95, v95
	v_cvt_pk_bf16_f32 v228, v92, v93
	v_cvt_pk_bf16_f32 v229, v94, v95
	s_waitcnt lgkmcnt(6)
	v_mfma_f32_32x32x16_bf16 v[32:47], v[248:251], v[222:225], v[32:47]
	v_add_f32_e32 v170, v170, v80
	v_add_f32_e32 v171, v171, v81
	v_add_f32_e32 v170, v170, v82
	v_add_f32_e32 v171, v171, v83
	v_mfma_f32_32x32x16_bf16 v[48:63], v[252:255], v[222:225], v[48:63]
	v_add_f32_e32 v170, v170, v84
	v_add_f32_e32 v171, v171, v85
	v_add_f32_e32 v170, v170, v86
	v_add_f32_e32 v171, v171, v87
	v_mfma_f32_32x32x16_bf16 v[32:47], v[214:217], v[226:229], v[32:47]
	v_add_f32_e32 v170, v170, v88
	v_add_f32_e32 v171, v171, v89
	v_add_f32_e32 v170, v170, v90
	v_add_f32_e32 v171, v171, v91
	v_mfma_f32_32x32x16_bf16 v[48:63], v[218:221], v[226:229], v[48:63]
	v_add_f32_e32 v170, v170, v92
	v_add_f32_e32 v171, v171, v93
	v_add_f32_e32 v170, v170, v94
	v_add_f32_e32 v171, v171, v95
	s_waitcnt vmcnt(0)
	s_add_i32 s4, s4, 1
	s_cmp_lt_u32 s4, s39
	s_cbranch_scc1 .Lp11_loop
